# prep: DFT-item staging loads hoisted (8 loads in flight, one wait) and V transposes with all 48 loads issued before the pack/store steps, on top of the last-layer item remap
# baseline (speedup 1.0000x reference)
; __device__ __forceinline__ void phase_prep(const Params& P, int l, unsigned char* lds) {
;     ...
;             float* U = (float*)lds;
;             float* U2 = U + 64 * 256;
; #pragma unroll
;             for (int rep = 0; rep < 4; ++rep) {
;                 const int id = tid + 512 * rep, tok = id >> 5, ch = id & 31;
;                 const u32x4 w = *(const u32x4*)(proj + (size_t)(r0 + tok) * INW + PD_U + 8 * ch);
;                 f32x4 a0 = (f32x4){bflo(w.x), bfhi(w.x), bflo(w.y), bfhi(w.y)}, a1 = (f32x4){bflo(w.z), bfhi(w.z), bflo(w.w), bfhi(w.w)};
;                 float* d = U + tok * 256 + 8 * ch;
;                 if (!is_ctx) {
;                     const int tg = t0 - CTX + tok, mt = (tg == 0) ? SEQ / 2 : SEQ - tg;
;                     const u32x4 m = *(const u32x4*)(proj + ((size_t)b * TT + CTX + mt) * INW + PD_U + 8 * ch);
;                     const f32x4 m0 = (f32x4){bflo(m.x), bfhi(m.x), bflo(m.y), bfhi(m.y)}, m1 = (f32x4){bflo(m.z), bfhi(m.z), bflo(m.w), bfhi(m.w)};
;                     float* d2 = U2 + tok * 256 + 8 * ch;
;                     if (tg == 0) { *(f32x4*)d2 = m0; *(f32x4*)(d2 + 4) = m1; }
;                     else { *(f32x4*)d2 = a0 - m0; *(f32x4*)(d2 + 4) = a1 - m1; a0 = a0 + m0; a1 = a1 + m1; }
;                 }
;                 *(f32x4*)d = a0; *(f32x4*)(d + 4) = a1;
.LBB0_232:
	s_cmpk_gt_i32 s64, 0xff
	s_cselect_b64 s[42:43], -1, 0
	s_cmpk_lt_i32 s64, 0x100
	s_cselect_b64 s[48:49], -1, 0
	s_andn2_b64 vcc, exec, s[38:39]
	s_mov_b64 s[38:39], -1
	s_cbranch_vccnz .LBB0_277
	v_mov_b64_e32 v[164:165], s[10:11]
	v_lshlrev_b32_e32 v166, 4, v44
	v_and_b32_e32 v166, 0x1f0, v166
	v_mov_b32_e32 v167, 0x1000
	v_add_u32_e32 v166, v166, v167
	v_mov_b32_e32 v167, 0
	s_mul_i32 s101, s36, 0x900
	s_add_u32 s101, s101, 0x100
	s_sub_u32 s100, s64, 0x100
	v_mov_b32_e32 v168, v44
	v_ashrrev_i32_e32 v168, 5, v168
	v_add_u32_e32 v169, s29, v168
	v_mad_u64_u32 v[170:171], vcc, v169, s23, v[164:165]
	v_lshl_add_u64 v[170:171], v[170:171], 0, v[166:167]
	global_load_dwordx4 v[132:135], v[170:171], off offset:1024
	s_cmp_eq_u64 s[42:43], 0
	s_cbranch_scc1 .Lvst_nom0
	v_add_u32_e32 v172, s100, v168
	v_sub_u32_e32 v173, 0x800, v172
	v_cmp_ne_u32_e32 vcc, 0, v172
	s_nop 1
	v_cndmask_b32_e32 v172, v242, v173, vcc
	v_add_u32_e32 v172, s101, v172
	v_mad_u64_u32 v[174:175], vcc, v172, s23, v[164:165]
	v_lshl_add_u64 v[174:175], v[174:175], 0, v[166:167]
	global_load_dwordx4 v[136:139], v[174:175], off offset:1024
.Lvst_nom0:
	v_add_u32_e32 v168, 0x200, v44
	v_ashrrev_i32_e32 v168, 5, v168
	v_add_u32_e32 v169, s29, v168
	v_mad_u64_u32 v[170:171], vcc, v169, s23, v[164:165]
	v_lshl_add_u64 v[170:171], v[170:171], 0, v[166:167]
	global_load_dwordx4 v[140:143], v[170:171], off offset:1024
	s_cmp_eq_u64 s[42:43], 0
	s_cbranch_scc1 .Lvst_nom1
	v_add_u32_e32 v172, s100, v168
	v_sub_u32_e32 v173, 0x800, v172
	v_cmp_ne_u32_e32 vcc, 0, v172
	s_nop 1
	v_cndmask_b32_e32 v172, v242, v173, vcc
	v_add_u32_e32 v172, s101, v172
	v_mad_u64_u32 v[174:175], vcc, v172, s23, v[164:165]
	v_lshl_add_u64 v[174:175], v[174:175], 0, v[166:167]
	global_load_dwordx4 v[144:147], v[174:175], off offset:1024
.Lvst_nom1:
	v_add_u32_e32 v168, 0x400, v44
	v_ashrrev_i32_e32 v168, 5, v168
	v_add_u32_e32 v169, s29, v168
	v_mad_u64_u32 v[170:171], vcc, v169, s23, v[164:165]
	v_lshl_add_u64 v[170:171], v[170:171], 0, v[166:167]
	global_load_dwordx4 v[148:151], v[170:171], off offset:1024
	s_cmp_eq_u64 s[42:43], 0
	s_cbranch_scc1 .Lvst_nom2
	v_add_u32_e32 v172, s100, v168
	v_sub_u32_e32 v173, 0x800, v172
	v_cmp_ne_u32_e32 vcc, 0, v172
	s_nop 1
	v_cndmask_b32_e32 v172, v242, v173, vcc
	v_add_u32_e32 v172, s101, v172
	v_mad_u64_u32 v[174:175], vcc, v172, s23, v[164:165]
	v_lshl_add_u64 v[174:175], v[174:175], 0, v[166:167]
	global_load_dwordx4 v[152:155], v[174:175], off offset:1024
.Lvst_nom2:
	v_add_u32_e32 v168, 0x600, v44
	v_ashrrev_i32_e32 v168, 5, v168
	v_add_u32_e32 v169, s29, v168
	v_mad_u64_u32 v[170:171], vcc, v169, s23, v[164:165]
	v_lshl_add_u64 v[170:171], v[170:171], 0, v[166:167]
	global_load_dwordx4 v[156:159], v[170:171], off offset:1024
	s_cmp_eq_u64 s[42:43], 0
	s_cbranch_scc1 .Lvst_nom3
	v_add_u32_e32 v172, s100, v168
	v_sub_u32_e32 v173, 0x800, v172
	v_cmp_ne_u32_e32 vcc, 0, v172
	s_nop 1
	v_cndmask_b32_e32 v172, v242, v173, vcc
	v_add_u32_e32 v172, s101, v172
	v_mad_u64_u32 v[174:175], vcc, v172, s23, v[164:165]
	v_lshl_add_u64 v[174:175], v[174:175], 0, v[166:167]
	global_load_dwordx4 v[160:163], v[174:175], off offset:1024
.Lvst_nom3:
	v_lshlrev_b32_e32 v25, 3, v44
	v_ashrrev_i32_e32 v8, 5, v44
	v_and_b32_e32 v17, 0xf8, v25
	v_add_u32_e32 v2, s29, v8
	v_mov_b64_e32 v[0:1], s[10:11]
	v_mad_i64_i32 v[0:1], s[12:13], v2, s23, v[0:1]
	v_lshlrev_b32_e32 v128, 1, v17
	v_lshl_add_u64 v[0:1], v[0:1], 0, v[128:129]
	s_movk_i32 s7, 0x1000
	v_add_co_u32_e32 v0, vcc, s7, v0
	s_add_i32 s13, 0, 0x10000
	s_nop 0
	v_addc_co_u32_e32 v1, vcc, 0, v1, vcc
	s_add_i32 s12, s64, 0xffffff00
	s_mul_i32 s18, s36, 0x900
	s_mul_hi_i32 s15, s36, 0x900
	s_add_u32 s50, s18, 0x100
	v_lshlrev_b32_e32 v18, 8, v8
	v_lshl_add_u32 v16, v17, 2, s13
	s_addc_u32 s51, s15, 0
	s_and_b64 vcc, exec, s[42:43]
	s_waitcnt vmcnt(0)
	v_mov_b32_e32 v4, v132
	v_mov_b32_e32 v5, v133
	v_mov_b32_e32 v6, v134
	v_mov_b32_e32 v7, v135
	v_lshlrev_b32_e32 v0, 16, v4
	v_and_b32_e32 v1, 0xffff0000, v4
	v_lshlrev_b32_e32 v2, 16, v5
	v_and_b32_e32 v3, 0xffff0000, v5
	v_lshlrev_b32_e32 v4, 16, v6
	v_and_b32_e32 v5, 0xffff0000, v6
	v_lshlrev_b32_e32 v6, 16, v7
	v_and_b32_e32 v7, 0xffff0000, v7
	s_cbranch_vccz .LBB0_239
	v_add_u32_e32 v8, s12, v8
	v_sub_u32_e32 v9, 0x800, v8
	v_cmp_ne_u32_e64 s[38:39], 0, v8
	v_mov_b64_e32 v[10:11], s[10:11]
	v_lshl_add_u32 v19, v18, 2, v16
	v_cndmask_b32_e64 v8, v242, v9, s[38:39]
	v_ashrrev_i32_e32 v9, 31, v8
	v_lshl_add_u64 v[8:9], s[50:51], 0, v[8:9]
	v_mad_u64_u32 v[10:11], s[18:19], v8, s23, v[10:11]
	v_mov_b32_e32 v8, v11
	v_mad_u64_u32 v[8:9], s[18:19], v9, s23, v[8:9]
	v_mov_b32_e32 v11, v8
	v_lshl_add_u64 v[8:9], v[10:11], 0, v[128:129]
	v_add_co_u32_e32 v8, vcc, s7, v8
	s_nop 1
	v_addc_co_u32_e32 v9, vcc, 0, v9, vcc
	v_mov_b32_e32 v8, v136
	v_mov_b32_e32 v9, v137
	v_mov_b32_e32 v10, v138
	v_mov_b32_e32 v11, v139
	v_lshlrev_b32_e32 v12, 16, v8
	v_and_b32_e32 v13, 0xffff0000, v8
	v_lshlrev_b32_e32 v14, 16, v9
	v_and_b32_e32 v15, 0xffff0000, v9
	v_lshlrev_b32_e32 v8, 16, v10
	v_and_b32_e32 v9, 0xffff0000, v10
	v_lshlrev_b32_e32 v10, 16, v11
	v_and_b32_e32 v11, 0xffff0000, v11
	s_and_saveexec_b64 s[18:19], s[38:39]
	s_xor_b64 s[38:39], exec, s[18:19]
	s_cbranch_execz .LBB0_236
	v_sub_f32_e32 v23, v3, v15
	v_sub_f32_e32 v22, v2, v14
	v_sub_f32_e32 v21, v1, v13
	v_sub_f32_e32 v20, v0, v12
	ds_write_b128 v19, v[20:23]
	v_sub_f32_e32 v23, v7, v11
	v_sub_f32_e32 v22, v6, v10
	v_sub_f32_e32 v21, v5, v9
	v_sub_f32_e32 v20, v4, v8
	ds_write_b128 v19, v[20:23] offset:16
	v_pk_add_f32 v[2:3], v[2:3], v[14:15]
	v_pk_add_f32 v[0:1], v[0:1], v[12:13]
	v_pk_add_f32 v[6:7], v[6:7], v[10:11]
	v_pk_add_f32 v[4:5], v[4:5], v[8:9]

; __device__ __forceinline__ void phase_prep(const Params& P, int l, unsigned char* lds) {
;     ...
;             for (int rep = 0; rep < 4; ++rep) {
;                 const int id = tid + 512 * rep, tok = id >> 5, ch = id & 31;
;                 const u32x4 w = *(const u32x4*)(proj + (size_t)(r0 + tok) * INW + PD_U + 8 * ch);
;                 f32x4 a0 = (f32x4){bflo(w.x), bfhi(w.x), bflo(w.y), bfhi(w.y)}, a1 = (f32x4){bflo(w.z), bfhi(w.z), bflo(w.w), bfhi(w.w)};
;                 float* d = U + tok * 256 + 8 * ch;
;                 if (!is_ctx) {
;                     const int tg = t0 - CTX + tok, mt = (tg == 0) ? SEQ / 2 : SEQ - tg;
;                     const u32x4 m = *(const u32x4*)(proj + ((size_t)b * TT + CTX + mt) * INW + PD_U + 8 * ch);
;                     const f32x4 m0 = (f32x4){bflo(m.x), bfhi(m.x), bflo(m.y), bfhi(m.y)}, m1 = (f32x4){bflo(m.z), bfhi(m.z), bflo(m.w), bfhi(m.w)};
;                     float* d2 = U2 + tok * 256 + 8 * ch;
;                     if (tg == 0) { *(f32x4*)d2 = m0; *(f32x4*)(d2 + 4) = m1; }
;                     else { *(f32x4*)d2 = a0 - m0; *(f32x4*)(d2 + 4) = a1 - m1; a0 = a0 + m0; a1 = a1 + m1; }
;                 }
;                 *(f32x4*)d = a0; *(f32x4*)(d + 4) = a1;
;             }
.LBB0_239:
	v_lshl_add_u32 v17, v17, 2, 0
	v_lshl_add_u32 v8, v18, 2, v17
	ds_write_b128 v8, v[0:3]
	ds_write_b128 v8, v[4:7] offset:16
	v_add_u32_e32 v0, 0x200, v44
	v_ashrrev_i32_e32 v8, 5, v0
	v_add_u32_e32 v2, s29, v8
	v_mov_b64_e32 v[0:1], s[10:11]
	v_mad_i64_i32 v[0:1], s[18:19], v2, s23, v[0:1]
	v_lshl_add_u64 v[0:1], v[0:1], 0, v[128:129]
	s_movk_i32 s13, 0x1000
	v_add_co_u32_e32 v0, vcc, s13, v0
	v_cndmask_b32_e64 v9, 0, 1, s[42:43]
	s_nop 0
	v_addc_co_u32_e32 v1, vcc, 0, v1, vcc
	v_lshlrev_b32_e32 v18, 8, v8
	v_cmp_ne_u32_e64 s[38:39], 1, v9
	s_andn2_b64 vcc, exec, s[42:43]
	v_mov_b32_e32 v4, v140
	v_mov_b32_e32 v5, v141
	v_mov_b32_e32 v6, v142
	v_mov_b32_e32 v7, v143
	v_lshlrev_b32_e32 v0, 16, v4
	v_and_b32_e32 v1, 0xffff0000, v4
	v_lshlrev_b32_e32 v2, 16, v5
	v_and_b32_e32 v3, 0xffff0000, v5
	v_lshlrev_b32_e32 v4, 16, v6
	v_and_b32_e32 v5, 0xffff0000, v6
	v_lshlrev_b32_e32 v6, 16, v7
	v_and_b32_e32 v7, 0xffff0000, v7
	s_cbranch_vccnz .LBB0_245
	v_add_u32_e32 v8, s12, v8
	v_sub_u32_e32 v9, 0x800, v8
	v_cmp_ne_u32_e32 vcc, 0, v8
	v_mov_b64_e32 v[10:11], s[10:11]
	v_lshl_add_u32 v19, v18, 2, v16
	v_cndmask_b32_e32 v8, v242, v9, vcc
	v_ashrrev_i32_e32 v9, 31, v8
	v_lshl_add_u64 v[8:9], s[50:51], 0, v[8:9]
	v_mad_u64_u32 v[10:11], s[18:19], v8, s23, v[10:11]
	v_mov_b32_e32 v8, v11
	v_mad_u64_u32 v[8:9], s[18:19], v9, s23, v[8:9]
	v_mov_b32_e32 v11, v8
	v_lshl_add_u64 v[8:9], v[10:11], 0, v[128:129]
	v_add_co_u32_e64 v8, s[40:41], s13, v8
	s_nop 1
	v_addc_co_u32_e64 v9, s[40:41], 0, v9, s[40:41]
	v_mov_b32_e32 v8, v144
	v_mov_b32_e32 v9, v145
	v_mov_b32_e32 v10, v146
	v_mov_b32_e32 v11, v147
	v_lshlrev_b32_e32 v12, 16, v8
	v_and_b32_e32 v13, 0xffff0000, v8
	v_lshlrev_b32_e32 v14, 16, v9
	v_and_b32_e32 v15, 0xffff0000, v9
	v_lshlrev_b32_e32 v8, 16, v10
	v_and_b32_e32 v9, 0xffff0000, v10
	v_lshlrev_b32_e32 v10, 16, v11
	v_and_b32_e32 v11, 0xffff0000, v11
	s_and_saveexec_b64 s[18:19], vcc
	s_xor_b64 s[40:41], exec, s[18:19]
	s_cbranch_execz .LBB0_242
	v_sub_f32_e32 v23, v3, v15
	v_sub_f32_e32 v22, v2, v14
	v_sub_f32_e32 v21, v1, v13
	v_sub_f32_e32 v20, v0, v12
	ds_write_b128 v19, v[20:23]
	v_sub_f32_e32 v23, v7, v11
	v_sub_f32_e32 v22, v6, v10
	v_sub_f32_e32 v21, v5, v9
	v_sub_f32_e32 v20, v4, v8
	v_pk_add_f32 v[2:3], v[2:3], v[14:15]
	v_pk_add_f32 v[0:1], v[0:1], v[12:13]
	v_pk_add_f32 v[6:7], v[6:7], v[10:11]
	v_pk_add_f32 v[4:5], v[4:5], v[8:9]
	ds_write_b128 v19, v[20:23] offset:16

; __device__ __forceinline__ void phase_prep(const Params& P, int l, unsigned char* lds) {
;     ...
;             for (int rep = 0; rep < 4; ++rep) {
;                 const int id = tid + 512 * rep, tok = id >> 5, ch = id & 31;
;                 const u32x4 w = *(const u32x4*)(proj + (size_t)(r0 + tok) * INW + PD_U + 8 * ch);
;                 f32x4 a0 = (f32x4){bflo(w.x), bfhi(w.x), bflo(w.y), bfhi(w.y)}, a1 = (f32x4){bflo(w.z), bfhi(w.z), bflo(w.w), bfhi(w.w)};
;                 float* d = U + tok * 256 + 8 * ch;
;                 if (!is_ctx) {
;                     const int tg = t0 - CTX + tok, mt = (tg == 0) ? SEQ / 2 : SEQ - tg;
;                     const u32x4 m = *(const u32x4*)(proj + ((size_t)b * TT + CTX + mt) * INW + PD_U + 8 * ch);
;                     const f32x4 m0 = (f32x4){bflo(m.x), bfhi(m.x), bflo(m.y), bfhi(m.y)}, m1 = (f32x4){bflo(m.z), bfhi(m.z), bflo(m.w), bfhi(m.w)};
;                     float* d2 = U2 + tok * 256 + 8 * ch;
;                     if (tg == 0) { *(f32x4*)d2 = m0; *(f32x4*)(d2 + 4) = m1; }
;                     else { *(f32x4*)d2 = a0 - m0; *(f32x4*)(d2 + 4) = a1 - m1; a0 = a0 + m0; a1 = a1 + m1; }
;                 }
;                 *(f32x4*)d = a0; *(f32x4*)(d + 4) = a1;
;             }
.LBB0_245:
	v_lshl_add_u32 v8, v18, 2, v17
	ds_write_b128 v8, v[0:3]
	ds_write_b128 v8, v[4:7] offset:16
	v_add_u32_e32 v0, 0x400, v44
	v_ashrrev_i32_e32 v8, 5, v0
	v_add_u32_e32 v2, s29, v8
	v_mov_b64_e32 v[0:1], s[10:11]
	v_mad_i64_i32 v[0:1], s[18:19], v2, s23, v[0:1]
	v_lshl_add_u64 v[0:1], v[0:1], 0, v[128:129]
	v_add_co_u32_e32 v0, vcc, 0x1000, v0
	v_lshlrev_b32_e32 v18, 8, v8
	s_nop 0
	v_addc_co_u32_e32 v1, vcc, 0, v1, vcc
	s_and_b64 vcc, exec, s[38:39]
	v_mov_b32_e32 v4, v148
	v_mov_b32_e32 v5, v149
	v_mov_b32_e32 v6, v150
	v_mov_b32_e32 v7, v151
	v_lshlrev_b32_e32 v0, 16, v4
	v_and_b32_e32 v1, 0xffff0000, v4
	v_lshlrev_b32_e32 v2, 16, v5
	v_and_b32_e32 v3, 0xffff0000, v5
	v_lshlrev_b32_e32 v4, 16, v6
	v_and_b32_e32 v5, 0xffff0000, v6
	v_lshlrev_b32_e32 v6, 16, v7
	v_and_b32_e32 v7, 0xffff0000, v7
	s_cbranch_vccnz .LBB0_251
	v_add_u32_e32 v8, s12, v8
	v_sub_u32_e32 v9, 0x800, v8
	v_cmp_ne_u32_e64 s[40:41], 0, v8
	v_mov_b64_e32 v[10:11], s[10:11]
	v_lshl_add_u32 v19, v18, 2, v16
	v_cndmask_b32_e64 v8, v242, v9, s[40:41]
	v_ashrrev_i32_e32 v9, 31, v8
	v_lshl_add_u64 v[8:9], s[50:51], 0, v[8:9]
	v_mad_u64_u32 v[10:11], s[18:19], v8, s23, v[10:11]
	v_mov_b32_e32 v8, v11
	v_mad_u64_u32 v[8:9], s[18:19], v9, s23, v[8:9]
	v_mov_b32_e32 v11, v8
	v_lshl_add_u64 v[8:9], v[10:11], 0, v[128:129]
	v_add_co_u32_e32 v8, vcc, s7, v8
	s_nop 1
	v_addc_co_u32_e32 v9, vcc, 0, v9, vcc
	v_mov_b32_e32 v8, v152
	v_mov_b32_e32 v9, v153
	v_mov_b32_e32 v10, v154
	v_mov_b32_e32 v11, v155
	v_lshlrev_b32_e32 v12, 16, v8
	v_and_b32_e32 v13, 0xffff0000, v8
	v_lshlrev_b32_e32 v14, 16, v9
	v_and_b32_e32 v15, 0xffff0000, v9
	v_lshlrev_b32_e32 v8, 16, v10
	v_and_b32_e32 v9, 0xffff0000, v10
	v_lshlrev_b32_e32 v10, 16, v11
	v_and_b32_e32 v11, 0xffff0000, v11
	s_and_saveexec_b64 s[18:19], s[40:41]
	s_xor_b64 s[40:41], exec, s[18:19]
	s_cbranch_execz .LBB0_248
	v_sub_f32_e32 v23, v3, v15
	v_sub_f32_e32 v22, v2, v14
	v_sub_f32_e32 v21, v1, v13
	v_sub_f32_e32 v20, v0, v12
	ds_write_b128 v19, v[20:23]
	v_sub_f32_e32 v23, v7, v11
	v_sub_f32_e32 v22, v6, v10
	v_sub_f32_e32 v21, v5, v9
	v_sub_f32_e32 v20, v4, v8
	v_pk_add_f32 v[2:3], v[2:3], v[14:15]
	v_pk_add_f32 v[0:1], v[0:1], v[12:13]
	v_pk_add_f32 v[6:7], v[6:7], v[10:11]
	v_pk_add_f32 v[4:5], v[4:5], v[8:9]
	ds_write_b128 v19, v[20:23] offset:16

; __device__ __forceinline__ void phase_prep(const Params& P, int l, unsigned char* lds) {
;     ...
;             for (int rep = 0; rep < 4; ++rep) {
;                 const int id = tid + 512 * rep, tok = id >> 5, ch = id & 31;
;                 const u32x4 w = *(const u32x4*)(proj + (size_t)(r0 + tok) * INW + PD_U + 8 * ch);
;                 f32x4 a0 = (f32x4){bflo(w.x), bfhi(w.x), bflo(w.y), bfhi(w.y)}, a1 = (f32x4){bflo(w.z), bfhi(w.z), bflo(w.w), bfhi(w.w)};
;                 float* d = U + tok * 256 + 8 * ch;
;                 if (!is_ctx) {
;                     const int tg = t0 - CTX + tok, mt = (tg == 0) ? SEQ / 2 : SEQ - tg;
;                     const u32x4 m = *(const u32x4*)(proj + ((size_t)b * TT + CTX + mt) * INW + PD_U + 8 * ch);
;                     const f32x4 m0 = (f32x4){bflo(m.x), bfhi(m.x), bflo(m.y), bfhi(m.y)}, m1 = (f32x4){bflo(m.z), bfhi(m.z), bflo(m.w), bfhi(m.w)};
;                     float* d2 = U2 + tok * 256 + 8 * ch;
;                     if (tg == 0) { *(f32x4*)d2 = m0; *(f32x4*)(d2 + 4) = m1; }
;                     else { *(f32x4*)d2 = a0 - m0; *(f32x4*)(d2 + 4) = a1 - m1; a0 = a0 + m0; a1 = a1 + m1; }
;                 }
;                 *(f32x4*)d = a0; *(f32x4*)(d + 4) = a1;
;             }
.LBB0_251:
	v_add_u32_e32 v8, 0x600, v44
	v_ashrrev_i32_e32 v8, 5, v8
	v_add_u32_e32 v9, s29, v8
	v_mov_b64_e32 v[10:11], s[10:11]
	v_mad_i64_i32 v[10:11], s[18:19], v9, s23, v[10:11]
	v_lshl_add_u64 v[10:11], v[10:11], 0, v[128:129]
	v_add_co_u32_e32 v10, vcc, 0x1000, v10
	v_lshl_add_u32 v9, v18, 2, v17
	s_nop 0
	v_addc_co_u32_e32 v11, vcc, 0, v11, vcc
	s_mov_b32 s15, 0
	ds_write_b128 v9, v[0:3]
	ds_write_b128 v9, v[4:7] offset:16
	s_and_b64 vcc, exec, s[38:39]
	v_lshlrev_b32_e32 v18, 8, v8
	v_mov_b32_e32 v10, v156
	v_mov_b32_e32 v11, v157
	v_mov_b32_e32 v12, v158
	v_mov_b32_e32 v13, v159
	v_lshlrev_b32_e32 v0, 16, v10
	v_and_b32_e32 v1, 0xffff0000, v10
	v_lshlrev_b32_e32 v2, 16, v11
	v_and_b32_e32 v3, 0xffff0000, v11
	v_lshlrev_b32_e32 v4, 16, v12
	v_and_b32_e32 v5, 0xffff0000, v12
	v_lshlrev_b32_e32 v6, 16, v13
	v_and_b32_e32 v7, 0xffff0000, v13
	s_cbranch_vccnz .LBB0_257
	v_add_u32_e32 v8, s12, v8
	v_sub_u32_e32 v9, 0x800, v8
	v_cmp_ne_u32_e32 vcc, 0, v8
	v_mov_b64_e32 v[10:11], s[10:11]
	v_lshl_add_u32 v16, v18, 2, v16
	v_cndmask_b32_e32 v8, v242, v9, vcc
	v_ashrrev_i32_e32 v9, 31, v8
	v_lshl_add_u64 v[8:9], s[50:51], 0, v[8:9]
	v_mad_u64_u32 v[10:11], s[12:13], v8, s23, v[10:11]
	v_mov_b32_e32 v8, v11
	v_mad_u64_u32 v[8:9], s[12:13], v9, s23, v[8:9]
	v_mov_b32_e32 v11, v8
	v_lshl_add_u64 v[8:9], v[10:11], 0, v[128:129]
	v_add_co_u32_e64 v8, s[38:39], s7, v8
	s_nop 1
	v_addc_co_u32_e64 v9, s[38:39], 0, v9, s[38:39]
	v_mov_b32_e32 v8, v160
	v_mov_b32_e32 v9, v161
	v_mov_b32_e32 v10, v162
	v_mov_b32_e32 v11, v163
	v_lshlrev_b32_e32 v12, 16, v8
	v_and_b32_e32 v13, 0xffff0000, v8
	v_lshlrev_b32_e32 v14, 16, v9
	v_and_b32_e32 v15, 0xffff0000, v9
	v_lshlrev_b32_e32 v8, 16, v10
	v_and_b32_e32 v9, 0xffff0000, v10
	v_lshlrev_b32_e32 v10, 16, v11
	v_and_b32_e32 v11, 0xffff0000, v11
	s_and_saveexec_b64 s[12:13], vcc
	s_xor_b64 s[38:39], exec, s[12:13]
	s_cbranch_execz .LBB0_254
	v_sub_f32_e32 v23, v3, v15
	v_sub_f32_e32 v22, v2, v14
	v_sub_f32_e32 v21, v1, v13
	v_sub_f32_e32 v20, v0, v12
	ds_write_b128 v16, v[20:23]
	v_sub_f32_e32 v23, v7, v11
	v_sub_f32_e32 v22, v6, v10
	v_sub_f32_e32 v21, v5, v9
	v_sub_f32_e32 v20, v4, v8
	v_pk_add_f32 v[2:3], v[2:3], v[14:15]
	v_pk_add_f32 v[0:1], v[0:1], v[12:13]
	v_pk_add_f32 v[6:7], v[6:7], v[10:11]
	v_pk_add_f32 v[4:5], v[4:5], v[8:9]
	ds_write_b128 v16, v[20:23] offset:16

; __device__ __forceinline__ void phase_prep(const Params& P, int l, unsigned char* lds) {
;     ...
; #pragma unroll 1
;             for (int rep = 0; rep < 6; ++rep) {
;                 const int id = tid + 512 * rep, cc = id % 384, ch = id / 384;
;                 const int col = (cc < 256) ? PA_V + cc : PC_V + (cc - 256);
;                 const bf16_t* p = proj + (size_t)(r0 + 8 * ch) * INW + col;
;                 unsigned e[8];
; #pragma unroll
;                 for (int j = 0; j < 8; ++j) e[j] = p[(size_t)j * INW];
;                 u32x4 o; o.x = e[0] | (e[1] << 16); o.y = e[2] | (e[3] << 16); o.z = e[4] | (e[5] << 16); o.w = e[6] | (e[7] << 16);
;                 bf16_t* dst = (cc < 256) ? (bf16_t*)(P.ws + WS_VTA) + ((size_t)b * 256 + cc) * TT : (bf16_t*)(P.ws + WS_VTC) + ((size_t)b * 128 + (cc - 256)) * TT;
;                 *(u32x4*)(dst + t0 + 8 * ch) = o;
;             }
.LBB0_290:
	v_mov_b32_e32 v0, v44
	v_mul_hi_i32 v1, v0, s26
	v_lshrrev_b32_e32 v2, 31, v1
	v_ashrrev_i32_e32 v1, 6, v1
	v_add_u32_e32 v1, v1, v2
	v_mul_i32_i24_e32 v2, 0x180, v1
	v_sub_u32_e32 v2, v0, v2
	v_cmp_gt_i32_e32 vcc, s21, v2
	v_mov_b32_e32 v0, 0x880
	v_mov_b32_e32 v3, 0x200
	v_cndmask_b32_e32 v0, v0, v3, vcc
	v_add_u32_e32 v128, v0, v2
	v_lshlrev_b32_e32 v0, 3, v1
	v_add_u32_e32 v1, s29, v0
	v_mov_b64_e32 v[4:5], s[10:11]
	v_mad_i64_i32 v[4:5], s[18:19], v1, s23, v[4:5]
	v_lshl_add_u64 v[4:5], v[128:129], 1, v[4:5]
	v_add_co_u32_e32 v6, vcc, 0x1000, v4
	global_load_ushort v132, v[4:5], off
	s_nop 0
	v_addc_co_u32_e32 v7, vcc, 0, v5, vcc
	global_load_ushort v133, v[6:7], off offset:1536
	v_add_co_u32_e32 v6, vcc, 0x2000, v4
	s_nop 1
	v_addc_co_u32_e32 v7, vcc, 0, v5, vcc
	global_load_ushort v134, v[6:7], off offset:3072
	v_add_co_u32_e32 v6, vcc, 0x4000, v4
	s_nop 1
	v_addc_co_u32_e32 v7, vcc, 0, v5, vcc
	global_load_ushort v135, v[6:7], off offset:512
	v_add_co_u32_e32 v6, vcc, 0x5000, v4
	s_nop 1
	v_addc_co_u32_e32 v7, vcc, 0, v5, vcc
	global_load_ushort v136, v[6:7], off offset:2048
	v_add_co_u32_e32 v6, vcc, 0x6000, v4
	s_nop 1
	v_addc_co_u32_e32 v7, vcc, 0, v5, vcc
	global_load_ushort v137, v[6:7], off offset:3584
	v_add_co_u32_e32 v6, vcc, 0x8000, v4
	s_nop 1
	v_addc_co_u32_e32 v7, vcc, 0, v5, vcc
	v_add_co_u32_e32 v4, vcc, 0x9000, v4
	global_load_ushort v138, v[6:7], off offset:1024
	s_nop 0
	v_addc_co_u32_e32 v5, vcc, 0, v5, vcc
	global_load_ushort v139, v[4:5], off offset:2560
	v_add_u32_e32 v0, 0x200, v44
	v_mul_hi_i32 v1, v0, s26
	v_lshrrev_b32_e32 v2, 31, v1
	v_ashrrev_i32_e32 v1, 6, v1
	v_add_u32_e32 v1, v1, v2
	v_mul_i32_i24_e32 v2, 0x180, v1
	v_sub_u32_e32 v2, v0, v2
	v_cmp_gt_i32_e32 vcc, s21, v2
	v_mov_b32_e32 v0, 0x880
	v_mov_b32_e32 v3, 0x200
	v_cndmask_b32_e32 v0, v0, v3, vcc
	v_add_u32_e32 v128, v0, v2
	v_lshlrev_b32_e32 v0, 3, v1
	v_add_u32_e32 v1, s29, v0
	v_mov_b64_e32 v[4:5], s[10:11]
	v_mad_i64_i32 v[4:5], s[18:19], v1, s23, v[4:5]
	v_lshl_add_u64 v[4:5], v[128:129], 1, v[4:5]
	v_add_co_u32_e32 v6, vcc, 0x1000, v4
	global_load_ushort v140, v[4:5], off
	s_nop 0
	v_addc_co_u32_e32 v7, vcc, 0, v5, vcc
	global_load_ushort v141, v[6:7], off offset:1536
	v_add_co_u32_e32 v6, vcc, 0x2000, v4
	s_nop 1
	v_addc_co_u32_e32 v7, vcc, 0, v5, vcc
	global_load_ushort v142, v[6:7], off offset:3072
	v_add_co_u32_e32 v6, vcc, 0x4000, v4
	s_nop 1
	v_addc_co_u32_e32 v7, vcc, 0, v5, vcc
	global_load_ushort v143, v[6:7], off offset:512
	v_add_co_u32_e32 v6, vcc, 0x5000, v4
	s_nop 1
	v_addc_co_u32_e32 v7, vcc, 0, v5, vcc
	global_load_ushort v144, v[6:7], off offset:2048
	v_add_co_u32_e32 v6, vcc, 0x6000, v4
	s_nop 1
	v_addc_co_u32_e32 v7, vcc, 0, v5, vcc
	global_load_ushort v145, v[6:7], off offset:3584
	v_add_co_u32_e32 v6, vcc, 0x8000, v4
	s_nop 1
	v_addc_co_u32_e32 v7, vcc, 0, v5, vcc
	v_add_co_u32_e32 v4, vcc, 0x9000, v4
	global_load_ushort v146, v[6:7], off offset:1024
	s_nop 0
	v_addc_co_u32_e32 v5, vcc, 0, v5, vcc
	global_load_ushort v147, v[4:5], off offset:2560
	v_add_u32_e32 v0, 0x400, v44
	v_mul_hi_i32 v1, v0, s26
	v_lshrrev_b32_e32 v2, 31, v1
	v_ashrrev_i32_e32 v1, 6, v1
	v_add_u32_e32 v1, v1, v2
	v_mul_i32_i24_e32 v2, 0x180, v1
	v_sub_u32_e32 v2, v0, v2
	v_cmp_gt_i32_e32 vcc, s21, v2
	v_mov_b32_e32 v0, 0x880
	v_mov_b32_e32 v3, 0x200
	v_cndmask_b32_e32 v0, v0, v3, vcc
	v_add_u32_e32 v128, v0, v2
	v_lshlrev_b32_e32 v0, 3, v1
	v_add_u32_e32 v1, s29, v0
	v_mov_b64_e32 v[4:5], s[10:11]
	v_mad_i64_i32 v[4:5], s[18:19], v1, s23, v[4:5]
	v_lshl_add_u64 v[4:5], v[128:129], 1, v[4:5]
	v_add_co_u32_e32 v6, vcc, 0x1000, v4
	global_load_ushort v148, v[4:5], off
	s_nop 0
	v_addc_co_u32_e32 v7, vcc, 0, v5, vcc
	global_load_ushort v149, v[6:7], off offset:1536
	v_add_co_u32_e32 v6, vcc, 0x2000, v4
	s_nop 1
	v_addc_co_u32_e32 v7, vcc, 0, v5, vcc
	global_load_ushort v150, v[6:7], off offset:3072
	v_add_co_u32_e32 v6, vcc, 0x4000, v4
	s_nop 1
	v_addc_co_u32_e32 v7, vcc, 0, v5, vcc
	global_load_ushort v151, v[6:7], off offset:512
	v_add_co_u32_e32 v6, vcc, 0x5000, v4
	s_nop 1
	v_addc_co_u32_e32 v7, vcc, 0, v5, vcc
	global_load_ushort v152, v[6:7], off offset:2048
	v_add_co_u32_e32 v6, vcc, 0x6000, v4
	s_nop 1
	v_addc_co_u32_e32 v7, vcc, 0, v5, vcc
	global_load_ushort v153, v[6:7], off offset:3584
	v_add_co_u32_e32 v6, vcc, 0x8000, v4
	s_nop 1
	v_addc_co_u32_e32 v7, vcc, 0, v5, vcc
	v_add_co_u32_e32 v4, vcc, 0x9000, v4
	global_load_ushort v154, v[6:7], off offset:1024
	s_nop 0
	v_addc_co_u32_e32 v5, vcc, 0, v5, vcc
	global_load_ushort v155, v[4:5], off offset:2560
	v_add_u32_e32 v0, 0x600, v44
	v_mul_hi_i32 v1, v0, s26
	v_lshrrev_b32_e32 v2, 31, v1
	v_ashrrev_i32_e32 v1, 6, v1
	v_add_u32_e32 v1, v1, v2
	v_mul_i32_i24_e32 v2, 0x180, v1
	v_sub_u32_e32 v2, v0, v2
	v_cmp_gt_i32_e32 vcc, s21, v2
	v_mov_b32_e32 v0, 0x880
	v_mov_b32_e32 v3, 0x200
	v_cndmask_b32_e32 v0, v0, v3, vcc
	v_add_u32_e32 v128, v0, v2
	v_lshlrev_b32_e32 v0, 3, v1
	v_add_u32_e32 v1, s29, v0
	v_mov_b64_e32 v[4:5], s[10:11]
	v_mad_i64_i32 v[4:5], s[18:19], v1, s23, v[4:5]
	v_lshl_add_u64 v[4:5], v[128:129], 1, v[4:5]
	v_add_co_u32_e32 v6, vcc, 0x1000, v4
	global_load_ushort v156, v[4:5], off
	s_nop 0
	v_addc_co_u32_e32 v7, vcc, 0, v5, vcc
	global_load_ushort v157, v[6:7], off offset:1536
	v_add_co_u32_e32 v6, vcc, 0x2000, v4
	s_nop 1
	v_addc_co_u32_e32 v7, vcc, 0, v5, vcc
	global_load_ushort v158, v[6:7], off offset:3072
	v_add_co_u32_e32 v6, vcc, 0x4000, v4
	s_nop 1
	v_addc_co_u32_e32 v7, vcc, 0, v5, vcc
	global_load_ushort v159, v[6:7], off offset:512
	v_add_co_u32_e32 v6, vcc, 0x5000, v4
	s_nop 1
	v_addc_co_u32_e32 v7, vcc, 0, v5, vcc
	global_load_ushort v160, v[6:7], off offset:2048
; __device__ __forceinline__ void phase_prep(const Params& P, int l, unsigned char* lds) {
;     ...
; #pragma unroll 1
;             for (int rep = 0; rep < 6; ++rep) {
;                 const int id = tid + 512 * rep, cc = id % 384, ch = id / 384;
;                 const int col = (cc < 256) ? PA_V + cc : PC_V + (cc - 256);
;                 const bf16_t* p = proj + (size_t)(r0 + 8 * ch) * INW + col;
;                 unsigned e[8];
; #pragma unroll
;                 for (int j = 0; j < 8; ++j) e[j] = p[(size_t)j * INW];
;                 u32x4 o; o.x = e[0] | (e[1] << 16); o.y = e[2] | (e[3] << 16); o.z = e[4] | (e[5] << 16); o.w = e[6] | (e[7] << 16);
;                 bf16_t* dst = (cc < 256) ? (bf16_t*)(P.ws + WS_VTA) + ((size_t)b * 256 + cc) * TT : (bf16_t*)(P.ws + WS_VTC) + ((size_t)b * 128 + (cc - 256)) * TT;
;                 *(u32x4*)(dst + t0 + 8 * ch) = o;
;             }
	v_add_co_u32_e32 v6, vcc, 0x6000, v4
	s_nop 1
	v_addc_co_u32_e32 v7, vcc, 0, v5, vcc
	global_load_ushort v161, v[6:7], off offset:3584
	v_add_co_u32_e32 v6, vcc, 0x8000, v4
	s_nop 1
	v_addc_co_u32_e32 v7, vcc, 0, v5, vcc
	v_add_co_u32_e32 v4, vcc, 0x9000, v4
	global_load_ushort v162, v[6:7], off offset:1024
	s_nop 0
	v_addc_co_u32_e32 v5, vcc, 0, v5, vcc
	global_load_ushort v163, v[4:5], off offset:2560
	v_add_u32_e32 v0, 0x800, v44
	v_mul_hi_i32 v1, v0, s26
	v_lshrrev_b32_e32 v2, 31, v1
	v_ashrrev_i32_e32 v1, 6, v1
	v_add_u32_e32 v1, v1, v2
	v_mul_i32_i24_e32 v2, 0x180, v1
	v_sub_u32_e32 v2, v0, v2
	v_cmp_gt_i32_e32 vcc, s21, v2
	v_mov_b32_e32 v0, 0x880
	v_mov_b32_e32 v3, 0x200
	v_cndmask_b32_e32 v0, v0, v3, vcc
	v_add_u32_e32 v128, v0, v2
	v_lshlrev_b32_e32 v0, 3, v1
	v_add_u32_e32 v1, s29, v0
	v_mov_b64_e32 v[4:5], s[10:11]
	v_mad_i64_i32 v[4:5], s[18:19], v1, s23, v[4:5]
	v_lshl_add_u64 v[4:5], v[128:129], 1, v[4:5]
	v_add_co_u32_e32 v6, vcc, 0x1000, v4
	global_load_ushort v164, v[4:5], off
	s_nop 0
	v_addc_co_u32_e32 v7, vcc, 0, v5, vcc
	global_load_ushort v165, v[6:7], off offset:1536
	v_add_co_u32_e32 v6, vcc, 0x2000, v4
	s_nop 1
	v_addc_co_u32_e32 v7, vcc, 0, v5, vcc
	global_load_ushort v166, v[6:7], off offset:3072
	v_add_co_u32_e32 v6, vcc, 0x4000, v4
	s_nop 1
	v_addc_co_u32_e32 v7, vcc, 0, v5, vcc
	global_load_ushort v167, v[6:7], off offset:512
	v_add_co_u32_e32 v6, vcc, 0x5000, v4
	s_nop 1
	v_addc_co_u32_e32 v7, vcc, 0, v5, vcc
	global_load_ushort v168, v[6:7], off offset:2048
	v_add_co_u32_e32 v6, vcc, 0x6000, v4
	s_nop 1
	v_addc_co_u32_e32 v7, vcc, 0, v5, vcc
	global_load_ushort v169, v[6:7], off offset:3584
	v_add_co_u32_e32 v6, vcc, 0x8000, v4
	s_nop 1
	v_addc_co_u32_e32 v7, vcc, 0, v5, vcc
	v_add_co_u32_e32 v4, vcc, 0x9000, v4
	global_load_ushort v170, v[6:7], off offset:1024
	s_nop 0
	v_addc_co_u32_e32 v5, vcc, 0, v5, vcc
	global_load_ushort v171, v[4:5], off offset:2560
	v_add_u32_e32 v0, 0xa00, v44
	v_mul_hi_i32 v1, v0, s26
	v_lshrrev_b32_e32 v2, 31, v1
	v_ashrrev_i32_e32 v1, 6, v1
	v_add_u32_e32 v1, v1, v2
	v_mul_i32_i24_e32 v2, 0x180, v1
	v_sub_u32_e32 v2, v0, v2
	v_cmp_gt_i32_e32 vcc, s21, v2
	v_mov_b32_e32 v0, 0x880
	v_mov_b32_e32 v3, 0x200
	v_cndmask_b32_e32 v0, v0, v3, vcc
	v_add_u32_e32 v128, v0, v2
	v_lshlrev_b32_e32 v0, 3, v1
	v_add_u32_e32 v1, s29, v0
	v_mov_b64_e32 v[4:5], s[10:11]
	v_mad_i64_i32 v[4:5], s[18:19], v1, s23, v[4:5]
	v_lshl_add_u64 v[4:5], v[128:129], 1, v[4:5]
	v_add_co_u32_e32 v6, vcc, 0x1000, v4
	global_load_ushort v172, v[4:5], off
	s_nop 0
	v_addc_co_u32_e32 v7, vcc, 0, v5, vcc
	global_load_ushort v173, v[6:7], off offset:1536
	v_add_co_u32_e32 v6, vcc, 0x2000, v4
	s_nop 1
	v_addc_co_u32_e32 v7, vcc, 0, v5, vcc
	global_load_ushort v174, v[6:7], off offset:3072
	v_add_co_u32_e32 v6, vcc, 0x4000, v4
	s_nop 1
	v_addc_co_u32_e32 v7, vcc, 0, v5, vcc
	global_load_ushort v175, v[6:7], off offset:512
	v_add_co_u32_e32 v6, vcc, 0x5000, v4
	s_nop 1
	v_addc_co_u32_e32 v7, vcc, 0, v5, vcc
	global_load_ushort v176, v[6:7], off offset:2048
	v_add_co_u32_e32 v6, vcc, 0x6000, v4
	s_nop 1
	v_addc_co_u32_e32 v7, vcc, 0, v5, vcc
	global_load_ushort v177, v[6:7], off offset:3584
	v_add_co_u32_e32 v6, vcc, 0x8000, v4
	s_nop 1
	v_addc_co_u32_e32 v7, vcc, 0, v5, vcc
	v_add_co_u32_e32 v4, vcc, 0x9000, v4
	global_load_ushort v178, v[6:7], off offset:1024
	s_nop 0
	v_addc_co_u32_e32 v5, vcc, 0, v5, vcc
	global_load_ushort v179, v[4:5], off offset:2560
	v_mov_b32_e32 v0, v44
	v_mul_hi_i32 v1, v0, s26
	v_lshrrev_b32_e32 v2, 31, v1
	v_ashrrev_i32_e32 v1, 6, v1
	v_add_u32_e32 v1, v1, v2
	v_mul_i32_i24_e32 v2, 0x180, v1
	v_sub_u32_e32 v2, v0, v2
	v_lshlrev_b32_e32 v0, 3, v1
	v_cmp_lt_i32_e32 vcc, s14, v2
	s_and_saveexec_b64 s[18:19], vcc
	s_xor_b64 s[42:43], exec, s[18:19]
	v_add_u32_e32 v128, 0xffffff00, v2
	v_lshl_add_u64 v[4:5], s[40:41], 0, v[128:129]
	s_or_saveexec_b64 s[42:43], s[42:43]
	v_mov_b64_e32 v[6:7], 0x17500000
	s_xor_b64 exec, exec, s[42:43]
	s_cbranch_execz .Lvt_dst0
	v_ashrrev_i32_e32 v3, 31, v2
	v_lshl_add_u64 v[4:5], s[36:37], 0, v[2:3]
	v_mov_b64_e32 v[6:7], 0x16300000
.Lvt_dst0:
	s_or_b64 exec, exec, s[42:43]
	s_waitcnt vmcnt(40)
	v_lshl_or_b32 v8, v133, 16, v132
	v_lshl_or_b32 v9, v135, 16, v134
	v_lshl_or_b32 v10, v137, 16, v136
	v_lshl_or_b32 v11, v139, 16, v138
	v_lshl_add_u64 v[2:3], s[0:1], 0, v[6:7]
	v_mad_u64_u32 v[2:3], s[18:19], v4, s27, v[2:3]
	v_mov_b32_e32 v4, v3
	v_mad_u64_u32 v[4:5], s[18:19], v5, s27, v[4:5]
	v_mov_b32_e32 v3, v4
	v_lshl_add_u64 v[2:3], s[38:39], 1, v[2:3]
	v_ashrrev_i32_e32 v1, 31, v0
	v_lshl_add_u64 v[0:1], v[0:1], 1, v[2:3]
	global_store_dwordx4 v[0:1], v[8:11], off
	v_add_u32_e32 v0, 0x200, v44
	v_mul_hi_i32 v1, v0, s26
	v_lshrrev_b32_e32 v2, 31, v1
	v_ashrrev_i32_e32 v1, 6, v1
	v_add_u32_e32 v1, v1, v2
	v_mul_i32_i24_e32 v2, 0x180, v1
	v_sub_u32_e32 v2, v0, v2
	v_lshlrev_b32_e32 v0, 3, v1
	v_cmp_lt_i32_e32 vcc, s14, v2
	s_and_saveexec_b64 s[18:19], vcc
	s_xor_b64 s[42:43], exec, s[18:19]
	v_add_u32_e32 v128, 0xffffff00, v2
	v_lshl_add_u64 v[4:5], s[40:41], 0, v[128:129]
	s_or_saveexec_b64 s[42:43], s[42:43]
	v_mov_b64_e32 v[6:7], 0x17500000
	s_xor_b64 exec, exec, s[42:43]
	s_cbranch_execz .Lvt_dst1
	v_ashrrev_i32_e32 v3, 31, v2
	v_lshl_add_u64 v[4:5], s[36:37], 0, v[2:3]
	v_mov_b64_e32 v[6:7], 0x16300000
; __device__ __forceinline__ void phase_prep(const Params& P, int l, unsigned char* lds) {
;     ...
; #pragma unroll 1
;             for (int rep = 0; rep < 6; ++rep) {
;                 const int id = tid + 512 * rep, cc = id % 384, ch = id / 384;
;                 const int col = (cc < 256) ? PA_V + cc : PC_V + (cc - 256);
;                 const bf16_t* p = proj + (size_t)(r0 + 8 * ch) * INW + col;
;                 unsigned e[8];
; #pragma unroll
;                 for (int j = 0; j < 8; ++j) e[j] = p[(size_t)j * INW];
;                 u32x4 o; o.x = e[0] | (e[1] << 16); o.y = e[2] | (e[3] << 16); o.z = e[4] | (e[5] << 16); o.w = e[6] | (e[7] << 16);
;                 bf16_t* dst = (cc < 256) ? (bf16_t*)(P.ws + WS_VTA) + ((size_t)b * 256 + cc) * TT : (bf16_t*)(P.ws + WS_VTC) + ((size_t)b * 128 + (cc - 256)) * TT;
;                 *(u32x4*)(dst + t0 + 8 * ch) = o;
;             }
.Lvt_dst1:
	s_or_b64 exec, exec, s[42:43]
	s_waitcnt vmcnt(33)
	v_lshl_or_b32 v8, v141, 16, v140
	v_lshl_or_b32 v9, v143, 16, v142
	v_lshl_or_b32 v10, v145, 16, v144
	v_lshl_or_b32 v11, v147, 16, v146
	v_lshl_add_u64 v[2:3], s[0:1], 0, v[6:7]
	v_mad_u64_u32 v[2:3], s[18:19], v4, s27, v[2:3]
	v_mov_b32_e32 v4, v3
	v_mad_u64_u32 v[4:5], s[18:19], v5, s27, v[4:5]
	v_mov_b32_e32 v3, v4
	v_lshl_add_u64 v[2:3], s[38:39], 1, v[2:3]
	v_ashrrev_i32_e32 v1, 31, v0
	v_lshl_add_u64 v[0:1], v[0:1], 1, v[2:3]
	global_store_dwordx4 v[0:1], v[8:11], off
	v_add_u32_e32 v0, 0x400, v44
	v_mul_hi_i32 v1, v0, s26
	v_lshrrev_b32_e32 v2, 31, v1
	v_ashrrev_i32_e32 v1, 6, v1
	v_add_u32_e32 v1, v1, v2
	v_mul_i32_i24_e32 v2, 0x180, v1
	v_sub_u32_e32 v2, v0, v2
	v_lshlrev_b32_e32 v0, 3, v1
	v_cmp_lt_i32_e32 vcc, s14, v2
	s_and_saveexec_b64 s[18:19], vcc
	s_xor_b64 s[42:43], exec, s[18:19]
	v_add_u32_e32 v128, 0xffffff00, v2
	v_lshl_add_u64 v[4:5], s[40:41], 0, v[128:129]
	s_or_saveexec_b64 s[42:43], s[42:43]
	v_mov_b64_e32 v[6:7], 0x17500000
	s_xor_b64 exec, exec, s[42:43]
	s_cbranch_execz .Lvt_dst2
	v_ashrrev_i32_e32 v3, 31, v2
	v_lshl_add_u64 v[4:5], s[36:37], 0, v[2:3]
	v_mov_b64_e32 v[6:7], 0x16300000
.Lvt_dst2:
	s_or_b64 exec, exec, s[42:43]
	s_waitcnt vmcnt(26)
	v_lshl_or_b32 v8, v149, 16, v148
	v_lshl_or_b32 v9, v151, 16, v150
	v_lshl_or_b32 v10, v153, 16, v152
	v_lshl_or_b32 v11, v155, 16, v154
	v_lshl_add_u64 v[2:3], s[0:1], 0, v[6:7]
	v_mad_u64_u32 v[2:3], s[18:19], v4, s27, v[2:3]
	v_mov_b32_e32 v4, v3
	v_mad_u64_u32 v[4:5], s[18:19], v5, s27, v[4:5]
	v_mov_b32_e32 v3, v4
	v_lshl_add_u64 v[2:3], s[38:39], 1, v[2:3]
	v_ashrrev_i32_e32 v1, 31, v0
	v_lshl_add_u64 v[0:1], v[0:1], 1, v[2:3]
	global_store_dwordx4 v[0:1], v[8:11], off
	v_add_u32_e32 v0, 0x600, v44
	v_mul_hi_i32 v1, v0, s26
	v_lshrrev_b32_e32 v2, 31, v1
	v_ashrrev_i32_e32 v1, 6, v1
	v_add_u32_e32 v1, v1, v2
	v_mul_i32_i24_e32 v2, 0x180, v1
	v_sub_u32_e32 v2, v0, v2
	v_lshlrev_b32_e32 v0, 3, v1
	v_cmp_lt_i32_e32 vcc, s14, v2
	s_and_saveexec_b64 s[18:19], vcc
	s_xor_b64 s[42:43], exec, s[18:19]
	v_add_u32_e32 v128, 0xffffff00, v2
	v_lshl_add_u64 v[4:5], s[40:41], 0, v[128:129]
	s_or_saveexec_b64 s[42:43], s[42:43]
	v_mov_b64_e32 v[6:7], 0x17500000
	s_xor_b64 exec, exec, s[42:43]
	s_cbranch_execz .Lvt_dst3
	v_ashrrev_i32_e32 v3, 31, v2
	v_lshl_add_u64 v[4:5], s[36:37], 0, v[2:3]
	v_mov_b64_e32 v[6:7], 0x16300000
.Lvt_dst3:
	s_or_b64 exec, exec, s[42:43]
	s_waitcnt vmcnt(19)
	v_lshl_or_b32 v8, v157, 16, v156
	v_lshl_or_b32 v9, v159, 16, v158
	v_lshl_or_b32 v10, v161, 16, v160
	v_lshl_or_b32 v11, v163, 16, v162
	v_lshl_add_u64 v[2:3], s[0:1], 0, v[6:7]
	v_mad_u64_u32 v[2:3], s[18:19], v4, s27, v[2:3]
	v_mov_b32_e32 v4, v3
	v_mad_u64_u32 v[4:5], s[18:19], v5, s27, v[4:5]
	v_mov_b32_e32 v3, v4
	v_lshl_add_u64 v[2:3], s[38:39], 1, v[2:3]
	v_ashrrev_i32_e32 v1, 31, v0
	v_lshl_add_u64 v[0:1], v[0:1], 1, v[2:3]
	global_store_dwordx4 v[0:1], v[8:11], off
	v_add_u32_e32 v0, 0x800, v44
	v_mul_hi_i32 v1, v0, s26
	v_lshrrev_b32_e32 v2, 31, v1
	v_ashrrev_i32_e32 v1, 6, v1
	v_add_u32_e32 v1, v1, v2
	v_mul_i32_i24_e32 v2, 0x180, v1
	v_sub_u32_e32 v2, v0, v2
	v_lshlrev_b32_e32 v0, 3, v1
	v_cmp_lt_i32_e32 vcc, s14, v2
	s_and_saveexec_b64 s[18:19], vcc
	s_xor_b64 s[42:43], exec, s[18:19]
	v_add_u32_e32 v128, 0xffffff00, v2
	v_lshl_add_u64 v[4:5], s[40:41], 0, v[128:129]
	s_or_saveexec_b64 s[42:43], s[42:43]
	v_mov_b64_e32 v[6:7], 0x17500000
	s_xor_b64 exec, exec, s[42:43]
	s_cbranch_execz .Lvt_dst4
	v_ashrrev_i32_e32 v3, 31, v2
	v_lshl_add_u64 v[4:5], s[36:37], 0, v[2:3]
	v_mov_b64_e32 v[6:7], 0x16300000
.Lvt_dst4:
	s_or_b64 exec, exec, s[42:43]
	s_waitcnt vmcnt(12)
	v_lshl_or_b32 v8, v165, 16, v164
	v_lshl_or_b32 v9, v167, 16, v166
	v_lshl_or_b32 v10, v169, 16, v168
	v_lshl_or_b32 v11, v171, 16, v170
	v_lshl_add_u64 v[2:3], s[0:1], 0, v[6:7]
	v_mad_u64_u32 v[2:3], s[18:19], v4, s27, v[2:3]
	v_mov_b32_e32 v4, v3
	v_mad_u64_u32 v[4:5], s[18:19], v5, s27, v[4:5]
	v_mov_b32_e32 v3, v4
	v_lshl_add_u64 v[2:3], s[38:39], 1, v[2:3]
	v_ashrrev_i32_e32 v1, 31, v0
	v_lshl_add_u64 v[0:1], v[0:1], 1, v[2:3]
	global_store_dwordx4 v[0:1], v[8:11], off
	v_add_u32_e32 v0, 0xa00, v44
	v_mul_hi_i32 v1, v0, s26
	v_lshrrev_b32_e32 v2, 31, v1
	v_ashrrev_i32_e32 v1, 6, v1
	v_add_u32_e32 v1, v1, v2
	v_mul_i32_i24_e32 v2, 0x180, v1
	v_sub_u32_e32 v2, v0, v2
	v_lshlrev_b32_e32 v0, 3, v1
	v_cmp_lt_i32_e32 vcc, s14, v2
	s_and_saveexec_b64 s[18:19], vcc
	s_xor_b64 s[42:43], exec, s[18:19]
	v_add_u32_e32 v128, 0xffffff00, v2
	v_lshl_add_u64 v[4:5], s[40:41], 0, v[128:129]
	s_or_saveexec_b64 s[42:43], s[42:43]
	v_mov_b64_e32 v[6:7], 0x17500000
	s_xor_b64 exec, exec, s[42:43]
	s_cbranch_execz .Lvt_dst5
	v_ashrrev_i32_e32 v3, 31, v2
	v_lshl_add_u64 v[4:5], s[36:37], 0, v[2:3]
	v_mov_b64_e32 v[6:7], 0x16300000
.Lvt_dst5:
	s_or_b64 exec, exec, s[42:43]
	s_waitcnt vmcnt(5)
	v_lshl_or_b32 v8, v173, 16, v172
	v_lshl_or_b32 v9, v175, 16, v174
	v_lshl_or_b32 v10, v177, 16, v176
	v_lshl_or_b32 v11, v179, 16, v178
	v_lshl_add_u64 v[2:3], s[0:1], 0, v[6:7]
	v_mad_u64_u32 v[2:3], s[18:19], v4, s27, v[2:3]
	v_mov_b32_e32 v4, v3
	v_mad_u64_u32 v[4:5], s[18:19], v5, s27, v[4:5]
	v_mov_b32_e32 v3, v4
	v_lshl_add_u64 v[2:3], s[38:39], 1, v[2:3]
	v_ashrrev_i32_e32 v1, 31, v0
	v_lshl_add_u64 v[0:1], v[0:1], 1, v[2:3]
	global_store_dwordx4 v[0:1], v[8:11], off
	s_branch .LBB0_227
